# P0 channel-DFT fold and w_f fold on the f32 matrix cores (v_mfma_f32_16x16x4_f32, f32 operands and accumulate) instead of per-lane f32 FMA loops fed by uniform LDS / vector loads
# speedup vs baseline: 1.0092x; 1.0092x over previous
.LBB0_65:
	v_ashrrev_i32_e32 v69, 31, v68
	v_writelane_b32 v245, s42, 4
	s_lshr_b32 s12, s86, 10
	s_bfe_u32 s13, s86, 0x20008
	s_bfe_u32 s14, s86, 0x30005
	s_and_b32 s15, s86, 31
	s_load_dwordx2 s[16:17], s[0:1], 0x18
	s_load_dwordx2 s[18:19], s[0:1], 0x80
	s_load_dwordx2 s[26:27], s[0:1], 0x30
	s_load_dwordx2 s[28:29], s[0:1], 0x38
	s_load_dwordx2 s[30:31], s[0:1], 0x40
	v_and_b32_e32 v3, 15, v68
	v_lshrrev_b32_e32 v4, 4, v68
	v_lshlrev_b32_e32 v5, 13, v3
	v_lshl_add_u32 v5, v4, 4, v5
	s_lshl_b32 s20, s12, 23
	s_lshl_b32 s21, s15, 18
	s_add_i32 s20, s20, s21
	s_lshl_b32 s21, s13, 9
	s_add_i32 s20, s20, s21
	s_addk_i32 s20, 0x1800
	s_waitcnt lgkmcnt(0)
	s_add_u32 s20, s16, s20
	s_addc_u32 s21, s17, 0
	s_add_u32 s22, s20, 0x20000
	s_addc_u32 s23, s21, 0
	global_load_dwordx4 v[6:9], v5, s[20:21] offset:0
	global_load_dwordx4 v[10:13], v5, s[20:21] offset:64
	global_load_dwordx4 v[14:17], v5, s[20:21] offset:128
	global_load_dwordx4 v[18:21], v5, s[20:21] offset:192
	global_load_dwordx4 v[22:25], v5, s[20:21] offset:256
	global_load_dwordx4 v[26:29], v5, s[20:21] offset:320
	global_load_dwordx4 v[30:33], v5, s[20:21] offset:384
	global_load_dwordx4 v[34:37], v5, s[20:21] offset:448
	global_load_dwordx4 v[70:73], v5, s[22:23] offset:0
	global_load_dwordx4 v[74:77], v5, s[22:23] offset:64
	global_load_dwordx4 v[78:81], v5, s[22:23] offset:128
	global_load_dwordx4 v[82:85], v5, s[22:23] offset:192
	global_load_dwordx4 v[86:89], v5, s[22:23] offset:256
	global_load_dwordx4 v[90:93], v5, s[22:23] offset:320
	global_load_dwordx4 v[94:97], v5, s[22:23] offset:384
	global_load_dwordx4 v[98:101], v5, s[22:23] offset:448
	v_lshl_add_u32 v142, s14, 4, v3
	v_lshrrev_b32_e32 v143, 1, v142
	v_and_b32_e32 v144, 1, v142
	v_cmp_eq_u32_e32 vcc, 1, v142
	v_mov_b32_e32 v145, 64
	v_cndmask_b32_e32 v143, v143, v145, vcc
	v_mov_b32_e32 v145, 0
	v_cndmask_b32_e32 v144, v144, v145, vcc
	v_lshlrev_b32_e32 v144, 9, v144
	v_add_u32_e32 v144, 0x11000, v144
	v_lshlrev_b32_e32 v145, 2, v4
	v_mul_u32_u24_e32 v145, v145, v143
	v_mov_b32_e32 v146, v145
	v_and_b32_e32 v146, 0x7f, v146
	v_lshl_add_u32 v146, v146, 2, v144
	ds_read_b32 v102, v146
	v_mul_u32_u24_e32 v147, 1, v143
	v_add_u32_e32 v147, v147, v145
	v_and_b32_e32 v147, 0x7f, v147
	v_lshl_add_u32 v147, v147, 2, v144
	ds_read_b32 v103, v147
	v_mul_u32_u24_e32 v148, 2, v143
	v_add_u32_e32 v148, v148, v145
	v_and_b32_e32 v148, 0x7f, v148
	v_lshl_add_u32 v148, v148, 2, v144
	ds_read_b32 v104, v148
	v_mul_u32_u24_e32 v149, 3, v143
	v_add_u32_e32 v149, v149, v145
	v_and_b32_e32 v149, 0x7f, v149
	v_lshl_add_u32 v149, v149, 2, v144
	ds_read_b32 v105, v149
	v_mul_u32_u24_e32 v146, 16, v143
	v_add_u32_e32 v146, v146, v145
	v_and_b32_e32 v146, 0x7f, v146
	v_lshl_add_u32 v146, v146, 2, v144
	ds_read_b32 v106, v146
	v_mul_u32_u24_e32 v147, 17, v143
	v_add_u32_e32 v147, v147, v145
	v_and_b32_e32 v147, 0x7f, v147
	v_lshl_add_u32 v147, v147, 2, v144
	ds_read_b32 v107, v147
	v_mul_u32_u24_e32 v148, 18, v143
	v_add_u32_e32 v148, v148, v145
	v_and_b32_e32 v148, 0x7f, v148
	v_lshl_add_u32 v148, v148, 2, v144
	ds_read_b32 v108, v148
	v_mul_u32_u24_e32 v149, 19, v143
	v_add_u32_e32 v149, v149, v145
	v_and_b32_e32 v149, 0x7f, v149
	v_lshl_add_u32 v149, v149, 2, v144
	ds_read_b32 v109, v149
	v_mul_u32_u24_e32 v146, 32, v143
	v_add_u32_e32 v146, v146, v145
	v_and_b32_e32 v146, 0x7f, v146
	v_lshl_add_u32 v146, v146, 2, v144
	ds_read_b32 v110, v146
	v_mul_u32_u24_e32 v147, 33, v143
	v_add_u32_e32 v147, v147, v145
	v_and_b32_e32 v147, 0x7f, v147
	v_lshl_add_u32 v147, v147, 2, v144
	ds_read_b32 v111, v147
	v_mul_u32_u24_e32 v148, 34, v143
	v_add_u32_e32 v148, v148, v145
	v_and_b32_e32 v148, 0x7f, v148
	v_lshl_add_u32 v148, v148, 2, v144
	ds_read_b32 v112, v148
	v_mul_u32_u24_e32 v149, 35, v143
	v_add_u32_e32 v149, v149, v145
	v_and_b32_e32 v149, 0x7f, v149
	v_lshl_add_u32 v149, v149, 2, v144
	ds_read_b32 v113, v149
	v_mul_u32_u24_e32 v146, 48, v143
	v_add_u32_e32 v146, v146, v145
	v_and_b32_e32 v146, 0x7f, v146
	v_lshl_add_u32 v146, v146, 2, v144
	ds_read_b32 v114, v146
	v_mul_u32_u24_e32 v147, 49, v143
	v_add_u32_e32 v147, v147, v145
	v_and_b32_e32 v147, 0x7f, v147
	v_lshl_add_u32 v147, v147, 2, v144
	ds_read_b32 v115, v147
	v_mul_u32_u24_e32 v148, 50, v143
	v_add_u32_e32 v148, v148, v145
	v_and_b32_e32 v148, 0x7f, v148
	v_lshl_add_u32 v148, v148, 2, v144
	ds_read_b32 v116, v148
	v_mul_u32_u24_e32 v149, 51, v143
	v_add_u32_e32 v149, v149, v145
	v_and_b32_e32 v149, 0x7f, v149
	v_lshl_add_u32 v149, v149, 2, v144
	ds_read_b32 v117, v149
	v_mul_u32_u24_e32 v146, 64, v143
	v_add_u32_e32 v146, v146, v145
	v_and_b32_e32 v146, 0x7f, v146
	v_lshl_add_u32 v146, v146, 2, v144
	ds_read_b32 v118, v146
	v_mul_u32_u24_e32 v147, 0x41, v143
	v_add_u32_e32 v147, v147, v145
	v_and_b32_e32 v147, 0x7f, v147
	v_lshl_add_u32 v147, v147, 2, v144
	ds_read_b32 v119, v147
	v_mul_u32_u24_e32 v148, 0x42, v143
	v_add_u32_e32 v148, v148, v145
	v_and_b32_e32 v148, 0x7f, v148
	v_lshl_add_u32 v148, v148, 2, v144
	ds_read_b32 v120, v148
	v_mul_u32_u24_e32 v149, 0x43, v143
	v_add_u32_e32 v149, v149, v145
	v_and_b32_e32 v149, 0x7f, v149
	v_lshl_add_u32 v149, v149, 2, v144
	ds_read_b32 v121, v149
	v_mul_u32_u24_e32 v146, 0x50, v143
	v_add_u32_e32 v146, v146, v145
	v_and_b32_e32 v146, 0x7f, v146
	v_lshl_add_u32 v146, v146, 2, v144
	ds_read_b32 v122, v146
	v_mul_u32_u24_e32 v147, 0x51, v143
	v_add_u32_e32 v147, v147, v145
	v_and_b32_e32 v147, 0x7f, v147
	v_lshl_add_u32 v147, v147, 2, v144
	ds_read_b32 v123, v147
	v_mul_u32_u24_e32 v148, 0x52, v143
	v_add_u32_e32 v148, v148, v145
	v_and_b32_e32 v148, 0x7f, v148
	v_lshl_add_u32 v148, v148, 2, v144
	ds_read_b32 v124, v148
	v_mul_u32_u24_e32 v149, 0x53, v143
	v_add_u32_e32 v149, v149, v145
	v_and_b32_e32 v149, 0x7f, v149
	v_lshl_add_u32 v149, v149, 2, v144
	ds_read_b32 v125, v149
	v_mul_u32_u24_e32 v146, 0x60, v143
	v_add_u32_e32 v146, v146, v145
	v_and_b32_e32 v146, 0x7f, v146
	v_lshl_add_u32 v146, v146, 2, v144
	ds_read_b32 v126, v146
	v_mul_u32_u24_e32 v147, 0x61, v143
	v_add_u32_e32 v147, v147, v145
	v_and_b32_e32 v147, 0x7f, v147
	v_lshl_add_u32 v147, v147, 2, v144
	ds_read_b32 v127, v147
	v_mul_u32_u24_e32 v148, 0x62, v143
	v_add_u32_e32 v148, v148, v145
	v_and_b32_e32 v148, 0x7f, v148
	v_lshl_add_u32 v148, v148, 2, v144
	ds_read_b32 v128, v148
	v_mul_u32_u24_e32 v149, 0x63, v143
	v_add_u32_e32 v149, v149, v145
	v_and_b32_e32 v149, 0x7f, v149
	v_lshl_add_u32 v149, v149, 2, v144
	ds_read_b32 v129, v149
	v_mul_u32_u24_e32 v146, 0x70, v143
	v_add_u32_e32 v146, v146, v145
	v_and_b32_e32 v146, 0x7f, v146
	v_lshl_add_u32 v146, v146, 2, v144
	ds_read_b32 v130, v146
	v_mul_u32_u24_e32 v147, 0x71, v143
	v_add_u32_e32 v147, v147, v145
	v_and_b32_e32 v147, 0x7f, v147
	v_lshl_add_u32 v147, v147, 2, v144
	ds_read_b32 v131, v147
	v_mul_u32_u24_e32 v148, 0x72, v143
	v_add_u32_e32 v148, v148, v145
	v_and_b32_e32 v148, 0x7f, v148
	v_lshl_add_u32 v148, v148, 2, v144
	ds_read_b32 v132, v148
	v_mul_u32_u24_e32 v149, 0x73, v143
	v_add_u32_e32 v149, v149, v145
	v_and_b32_e32 v149, 0x7f, v149
	v_lshl_add_u32 v149, v149, 2, v144
	ds_read_b32 v133, v149
	s_mul_i32 s24, s12, 0x1800000
	s_add_u32 s24, s24, 0x500000
	s_lshl_b32 s25, s13, 18
	s_add_u32 s24, s24, s25
	s_lshl_b32 s25, s14, 15
	s_add_u32 s24, s24, s25
	s_lshl_b32 s25, s15, 6
	s_add_u32 s24, s24, s25
	s_add_u32 s24, s18, s24
	s_addc_u32 s25, s19, 0
	v_lshlrev_b32_e32 v150, 11, v3
	v_lshl_add_u32 v150, v4, 3, v150
	s_waitcnt vmcnt(0) lgkmcnt(0)
	v_mfma_f32_16x16x4_f32 v[134:137], v6, v102, 0
	v_mfma_f32_16x16x4_f32 v[138:141], v70, v102, 0
	v_mfma_f32_16x16x4_f32 v[134:137], v7, v103, v[134:137]
	v_mfma_f32_16x16x4_f32 v[138:141], v71, v103, v[138:141]
	v_mfma_f32_16x16x4_f32 v[134:137], v8, v104, v[134:137]
	v_mfma_f32_16x16x4_f32 v[138:141], v72, v104, v[138:141]
	v_mfma_f32_16x16x4_f32 v[134:137], v9, v105, v[134:137]
	v_mfma_f32_16x16x4_f32 v[138:141], v73, v105, v[138:141]
	v_mfma_f32_16x16x4_f32 v[134:137], v10, v106, v[134:137]
	v_mfma_f32_16x16x4_f32 v[138:141], v74, v106, v[138:141]
	v_mfma_f32_16x16x4_f32 v[134:137], v11, v107, v[134:137]
	v_mfma_f32_16x16x4_f32 v[138:141], v75, v107, v[138:141]
	v_mfma_f32_16x16x4_f32 v[134:137], v12, v108, v[134:137]
	v_mfma_f32_16x16x4_f32 v[138:141], v76, v108, v[138:141]
	v_mfma_f32_16x16x4_f32 v[134:137], v13, v109, v[134:137]
	v_mfma_f32_16x16x4_f32 v[138:141], v77, v109, v[138:141]
	v_mfma_f32_16x16x4_f32 v[134:137], v14, v110, v[134:137]
	v_mfma_f32_16x16x4_f32 v[138:141], v78, v110, v[138:141]
	v_mfma_f32_16x16x4_f32 v[134:137], v15, v111, v[134:137]
	v_mfma_f32_16x16x4_f32 v[138:141], v79, v111, v[138:141]
	v_mfma_f32_16x16x4_f32 v[134:137], v16, v112, v[134:137]
	v_mfma_f32_16x16x4_f32 v[138:141], v80, v112, v[138:141]
	v_mfma_f32_16x16x4_f32 v[134:137], v17, v113, v[134:137]
	v_mfma_f32_16x16x4_f32 v[138:141], v81, v113, v[138:141]
	v_mfma_f32_16x16x4_f32 v[134:137], v18, v114, v[134:137]
	v_mfma_f32_16x16x4_f32 v[138:141], v82, v114, v[138:141]
	v_mfma_f32_16x16x4_f32 v[134:137], v19, v115, v[134:137]
	v_mfma_f32_16x16x4_f32 v[138:141], v83, v115, v[138:141]
	v_mfma_f32_16x16x4_f32 v[134:137], v20, v116, v[134:137]
	v_mfma_f32_16x16x4_f32 v[138:141], v84, v116, v[138:141]
	v_mfma_f32_16x16x4_f32 v[134:137], v21, v117, v[134:137]
	v_mfma_f32_16x16x4_f32 v[138:141], v85, v117, v[138:141]
	v_mfma_f32_16x16x4_f32 v[134:137], v22, v118, v[134:137]
	v_mfma_f32_16x16x4_f32 v[138:141], v86, v118, v[138:141]
	v_mfma_f32_16x16x4_f32 v[134:137], v23, v119, v[134:137]
	v_mfma_f32_16x16x4_f32 v[138:141], v87, v119, v[138:141]
	v_mfma_f32_16x16x4_f32 v[134:137], v24, v120, v[134:137]
	v_mfma_f32_16x16x4_f32 v[138:141], v88, v120, v[138:141]
	v_mfma_f32_16x16x4_f32 v[134:137], v25, v121, v[134:137]
	v_mfma_f32_16x16x4_f32 v[138:141], v89, v121, v[138:141]
	v_mfma_f32_16x16x4_f32 v[134:137], v26, v122, v[134:137]
	v_mfma_f32_16x16x4_f32 v[138:141], v90, v122, v[138:141]
	v_mfma_f32_16x16x4_f32 v[134:137], v27, v123, v[134:137]
	v_mfma_f32_16x16x4_f32 v[138:141], v91, v123, v[138:141]
	v_mfma_f32_16x16x4_f32 v[134:137], v28, v124, v[134:137]
	v_mfma_f32_16x16x4_f32 v[138:141], v92, v124, v[138:141]
	v_mfma_f32_16x16x4_f32 v[134:137], v29, v125, v[134:137]
	v_mfma_f32_16x16x4_f32 v[138:141], v93, v125, v[138:141]
	v_mfma_f32_16x16x4_f32 v[134:137], v30, v126, v[134:137]
	v_mfma_f32_16x16x4_f32 v[138:141], v94, v126, v[138:141]
	v_mfma_f32_16x16x4_f32 v[134:137], v31, v127, v[134:137]
	v_mfma_f32_16x16x4_f32 v[138:141], v95, v127, v[138:141]
	v_mfma_f32_16x16x4_f32 v[134:137], v32, v128, v[134:137]
	v_mfma_f32_16x16x4_f32 v[138:141], v96, v128, v[138:141]
	v_mfma_f32_16x16x4_f32 v[134:137], v33, v129, v[134:137]
	v_mfma_f32_16x16x4_f32 v[138:141], v97, v129, v[138:141]
	v_mfma_f32_16x16x4_f32 v[134:137], v34, v130, v[134:137]
	v_mfma_f32_16x16x4_f32 v[138:141], v98, v130, v[138:141]
	v_mfma_f32_16x16x4_f32 v[134:137], v35, v131, v[134:137]
	v_mfma_f32_16x16x4_f32 v[138:141], v99, v131, v[138:141]
	v_mfma_f32_16x16x4_f32 v[134:137], v36, v132, v[134:137]
	v_mfma_f32_16x16x4_f32 v[138:141], v100, v132, v[138:141]
	v_mfma_f32_16x16x4_f32 v[134:137], v37, v133, v[134:137]
	v_mfma_f32_16x16x4_f32 v[138:141], v101, v133, v[138:141]
	s_nop 15
	s_nop 7
	v_cvt_pk_bf16_f32 v146, v134, v135
	v_cvt_pk_bf16_f32 v147, v136, v137
	v_cvt_pk_bf16_f32 v148, v138, v139
	v_cvt_pk_bf16_f32 v149, v140, v141
	global_store_dwordx2 v150, v[146:147], s[24:25]
	global_store_dwordx2 v150, v[148:149], s[24:25] offset:32
	s_lshl_b32 s20, s12, 2
	s_add_i32 s20, s20, s13
	s_lshl_b32 s20, s20, 16
	s_lshl_b32 s21, s14, 13
	s_add_i32 s20, s20, s21
	s_add_u32 s20, s26, s20
	s_addc_u32 s21, s27, 0
	v_lshlrev_b32_e32 v5, 9, v3
	v_lshl_add_u32 v5, v4, 4, v5
	global_load_dwordx4 v[6:9], v5, s[20:21] offset:0
	global_load_dwordx4 v[10:13], v5, s[20:21] offset:64
	global_load_dwordx4 v[14:17], v5, s[20:21] offset:128
	global_load_dwordx4 v[18:21], v5, s[20:21] offset:192
	global_load_dwordx4 v[22:25], v5, s[20:21] offset:256
	global_load_dwordx4 v[26:29], v5, s[20:21] offset:320
	global_load_dwordx4 v[30:33], v5, s[20:21] offset:384
	global_load_dwordx4 v[34:37], v5, s[20:21] offset:448
	s_lshl_b32 s34, s12, 22
	s_lshl_b32 s35, s13, 19
	s_add_i32 s34, s34, s35
	s_add_i32 s34, s34, 0x200000
	s_lshl_b32 s35, s15, 7
	s_add_i32 s34, s34, s35
	s_add_u32 s34, s30, s34
	s_addc_u32 s35, s31, 0
	v_lshlrev_b32_e32 v151, 14, v4
	v_lshl_add_u32 v151, v3, 2, v151
	s_mov_b64 s[36:37], s[34:35]
	global_load_dword v70, v151, s[36:37]
	global_load_dword v102, v151, s[36:37] offset:64
	s_add_u32 s36, s34, 0x1000
	s_addc_u32 s37, s35, 0
	global_load_dword v71, v151, s[36:37]
	global_load_dword v103, v151, s[36:37] offset:64
	s_add_u32 s36, s34, 0x2000
	s_addc_u32 s37, s35, 0
	global_load_dword v72, v151, s[36:37]
	global_load_dword v104, v151, s[36:37] offset:64
	s_add_u32 s36, s34, 0x3000
	s_addc_u32 s37, s35, 0
	global_load_dword v73, v151, s[36:37]
	global_load_dword v105, v151, s[36:37] offset:64
	s_add_u32 s36, s34, 0x10000
	s_addc_u32 s37, s35, 0
	global_load_dword v74, v151, s[36:37]
	global_load_dword v106, v151, s[36:37] offset:64
	s_add_u32 s36, s34, 0x11000
	s_addc_u32 s37, s35, 0
	global_load_dword v75, v151, s[36:37]
	global_load_dword v107, v151, s[36:37] offset:64
	s_add_u32 s36, s34, 0x12000
	s_addc_u32 s37, s35, 0
	global_load_dword v76, v151, s[36:37]
	global_load_dword v108, v151, s[36:37] offset:64
	s_add_u32 s36, s34, 0x13000
	s_addc_u32 s37, s35, 0
	global_load_dword v77, v151, s[36:37]
	global_load_dword v109, v151, s[36:37] offset:64
	s_add_u32 s36, s34, 0x20000
	s_addc_u32 s37, s35, 0
	global_load_dword v78, v151, s[36:37]
	global_load_dword v110, v151, s[36:37] offset:64
	s_add_u32 s36, s34, 0x21000
	s_addc_u32 s37, s35, 0
	global_load_dword v79, v151, s[36:37]
	global_load_dword v111, v151, s[36:37] offset:64
	s_add_u32 s36, s34, 0x22000
	s_addc_u32 s37, s35, 0
	global_load_dword v80, v151, s[36:37]
	global_load_dword v112, v151, s[36:37] offset:64
	s_add_u32 s36, s34, 0x23000
	s_addc_u32 s37, s35, 0
	global_load_dword v81, v151, s[36:37]
	global_load_dword v113, v151, s[36:37] offset:64
	s_add_u32 s36, s34, 0x30000
	s_addc_u32 s37, s35, 0
	global_load_dword v82, v151, s[36:37]
	global_load_dword v114, v151, s[36:37] offset:64
	s_add_u32 s36, s34, 0x31000
	s_addc_u32 s37, s35, 0
	global_load_dword v83, v151, s[36:37]
	global_load_dword v115, v151, s[36:37] offset:64
	s_add_u32 s36, s34, 0x32000
	s_addc_u32 s37, s35, 0
	global_load_dword v84, v151, s[36:37]
	global_load_dword v116, v151, s[36:37] offset:64
	s_add_u32 s36, s34, 0x33000
	s_addc_u32 s37, s35, 0
	global_load_dword v85, v151, s[36:37]
	global_load_dword v117, v151, s[36:37] offset:64
	s_cmp_lg_u32 s14, 0
	s_cbranch_scc1 .Lp0c_nobf
	s_lshl_b32 s38, s12, 11
	s_lshl_b32 s39, s13, 9
	s_add_i32 s38, s38, s39
	s_add_u32 s38, s28, s38
	s_addc_u32 s39, s29, 0
	v_lshlrev_b32_e32 v152, 4, v4
	global_load_dwordx4 v[38:41], v152, s[38:39] offset:0
	global_load_dwordx4 v[42:45], v152, s[38:39] offset:64
	global_load_dwordx4 v[46:49], v152, s[38:39] offset:128
	global_load_dwordx4 v[50:53], v152, s[38:39] offset:192
	global_load_dwordx4 v[54:57], v152, s[38:39] offset:256
	global_load_dwordx4 v[58:61], v152, s[38:39] offset:320
	global_load_dwordx4 v[62:65], v152, s[38:39] offset:384
	global_load_dwordx4 v[142:145], v152, s[38:39] offset:448
.Lp0c_nobf:
	s_waitcnt vmcnt(20)
	s_add_u32 s36, s34, 0x40000
	s_addc_u32 s37, s35, 0
	global_load_dword v86, v151, s[36:37]
	global_load_dword v118, v151, s[36:37] offset:64
	s_add_u32 s36, s34, 0x41000
	s_addc_u32 s37, s35, 0
	global_load_dword v87, v151, s[36:37]
	global_load_dword v119, v151, s[36:37] offset:64
	s_add_u32 s36, s34, 0x42000
	s_addc_u32 s37, s35, 0
	global_load_dword v88, v151, s[36:37]
	global_load_dword v120, v151, s[36:37] offset:64
	s_add_u32 s36, s34, 0x43000
	s_addc_u32 s37, s35, 0
	global_load_dword v89, v151, s[36:37]
	global_load_dword v121, v151, s[36:37] offset:64
	s_add_u32 s36, s34, 0x50000
	s_addc_u32 s37, s35, 0
	global_load_dword v90, v151, s[36:37]
	global_load_dword v122, v151, s[36:37] offset:64
	s_add_u32 s36, s34, 0x51000
	s_addc_u32 s37, s35, 0
	global_load_dword v91, v151, s[36:37]
	global_load_dword v123, v151, s[36:37] offset:64
	s_add_u32 s36, s34, 0x52000
	s_addc_u32 s37, s35, 0
	global_load_dword v92, v151, s[36:37]
	global_load_dword v124, v151, s[36:37] offset:64
	s_add_u32 s36, s34, 0x53000
	s_addc_u32 s37, s35, 0
	global_load_dword v93, v151, s[36:37]
	global_load_dword v125, v151, s[36:37] offset:64
	s_add_u32 s36, s34, 0x60000
	s_addc_u32 s37, s35, 0
	global_load_dword v94, v151, s[36:37]
	global_load_dword v126, v151, s[36:37] offset:64
	s_add_u32 s36, s34, 0x61000
	s_addc_u32 s37, s35, 0
	global_load_dword v95, v151, s[36:37]
	global_load_dword v127, v151, s[36:37] offset:64
	s_add_u32 s36, s34, 0x62000
	s_addc_u32 s37, s35, 0
	global_load_dword v96, v151, s[36:37]
	global_load_dword v128, v151, s[36:37] offset:64
	s_add_u32 s36, s34, 0x63000
	s_addc_u32 s37, s35, 0
	global_load_dword v97, v151, s[36:37]
	global_load_dword v129, v151, s[36:37] offset:64
	s_add_u32 s36, s34, 0x70000
	s_addc_u32 s37, s35, 0
	global_load_dword v98, v151, s[36:37]
	global_load_dword v130, v151, s[36:37] offset:64
	s_add_u32 s36, s34, 0x71000
	s_addc_u32 s37, s35, 0
	global_load_dword v99, v151, s[36:37]
	global_load_dword v131, v151, s[36:37] offset:64
	s_add_u32 s36, s34, 0x72000
	s_addc_u32 s37, s35, 0
	global_load_dword v100, v151, s[36:37]
	global_load_dword v132, v151, s[36:37] offset:64
	s_add_u32 s36, s34, 0x73000
	s_addc_u32 s37, s35, 0
	global_load_dword v101, v151, s[36:37]
	global_load_dword v133, v151, s[36:37] offset:64
	s_mul_i32 s40, s12, 0x1800000
	s_add_u32 s40, s40, 0x700400
	s_lshl_b32 s41, s15, 16
	s_add_u32 s40, s40, s41
	s_lshl_b32 s41, s13, 8
	s_add_u32 s40, s40, s41
	s_lshl_b32 s41, s14, 5
	s_add_u32 s40, s40, s41
	s_add_u32 s40, s18, s40
	s_addc_u32 s41, s19, 0
	s_add_u32 s44, s40, 0x8000
	s_addc_u32 s45, s41, 0
	s_waitcnt vmcnt(0)
	v_mfma_f32_16x16x4_f32 v[134:137], v6, v70, 0
	v_mfma_f32_16x16x4_f32 v[138:141], v6, v102, 0
	v_mfma_f32_16x16x4_f32 v[134:137], v7, v71, v[134:137]
	v_mfma_f32_16x16x4_f32 v[138:141], v7, v103, v[138:141]
	v_mfma_f32_16x16x4_f32 v[134:137], v8, v72, v[134:137]
	v_mfma_f32_16x16x4_f32 v[138:141], v8, v104, v[138:141]
	v_mfma_f32_16x16x4_f32 v[134:137], v9, v73, v[134:137]
	v_mfma_f32_16x16x4_f32 v[138:141], v9, v105, v[138:141]
	v_mfma_f32_16x16x4_f32 v[134:137], v10, v74, v[134:137]
	v_mfma_f32_16x16x4_f32 v[138:141], v10, v106, v[138:141]
	v_mfma_f32_16x16x4_f32 v[134:137], v11, v75, v[134:137]
	v_mfma_f32_16x16x4_f32 v[138:141], v11, v107, v[138:141]
	v_mfma_f32_16x16x4_f32 v[134:137], v12, v76, v[134:137]
	v_mfma_f32_16x16x4_f32 v[138:141], v12, v108, v[138:141]
	v_mfma_f32_16x16x4_f32 v[134:137], v13, v77, v[134:137]
	v_mfma_f32_16x16x4_f32 v[138:141], v13, v109, v[138:141]
	v_mfma_f32_16x16x4_f32 v[134:137], v14, v78, v[134:137]
	v_mfma_f32_16x16x4_f32 v[138:141], v14, v110, v[138:141]
	v_mfma_f32_16x16x4_f32 v[134:137], v15, v79, v[134:137]
	v_mfma_f32_16x16x4_f32 v[138:141], v15, v111, v[138:141]
	v_mfma_f32_16x16x4_f32 v[134:137], v16, v80, v[134:137]
	v_mfma_f32_16x16x4_f32 v[138:141], v16, v112, v[138:141]
	v_mfma_f32_16x16x4_f32 v[134:137], v17, v81, v[134:137]
	v_mfma_f32_16x16x4_f32 v[138:141], v17, v113, v[138:141]
	v_mfma_f32_16x16x4_f32 v[134:137], v18, v82, v[134:137]
	v_mfma_f32_16x16x4_f32 v[138:141], v18, v114, v[138:141]
	v_mfma_f32_16x16x4_f32 v[134:137], v19, v83, v[134:137]
	v_mfma_f32_16x16x4_f32 v[138:141], v19, v115, v[138:141]
	v_mfma_f32_16x16x4_f32 v[134:137], v20, v84, v[134:137]
	v_mfma_f32_16x16x4_f32 v[138:141], v20, v116, v[138:141]
	v_mfma_f32_16x16x4_f32 v[134:137], v21, v85, v[134:137]
	v_mfma_f32_16x16x4_f32 v[138:141], v21, v117, v[138:141]
	v_mfma_f32_16x16x4_f32 v[134:137], v22, v86, v[134:137]
	v_mfma_f32_16x16x4_f32 v[138:141], v22, v118, v[138:141]
	v_mfma_f32_16x16x4_f32 v[134:137], v23, v87, v[134:137]
	v_mfma_f32_16x16x4_f32 v[138:141], v23, v119, v[138:141]
	v_mfma_f32_16x16x4_f32 v[134:137], v24, v88, v[134:137]
	v_mfma_f32_16x16x4_f32 v[138:141], v24, v120, v[138:141]
	v_mfma_f32_16x16x4_f32 v[134:137], v25, v89, v[134:137]
	v_mfma_f32_16x16x4_f32 v[138:141], v25, v121, v[138:141]
	v_mfma_f32_16x16x4_f32 v[134:137], v26, v90, v[134:137]
	v_mfma_f32_16x16x4_f32 v[138:141], v26, v122, v[138:141]
	v_mfma_f32_16x16x4_f32 v[134:137], v27, v91, v[134:137]
	v_mfma_f32_16x16x4_f32 v[138:141], v27, v123, v[138:141]
	v_mfma_f32_16x16x4_f32 v[134:137], v28, v92, v[134:137]
	v_mfma_f32_16x16x4_f32 v[138:141], v28, v124, v[138:141]
	v_mfma_f32_16x16x4_f32 v[134:137], v29, v93, v[134:137]
	v_mfma_f32_16x16x4_f32 v[138:141], v29, v125, v[138:141]
	v_mfma_f32_16x16x4_f32 v[134:137], v30, v94, v[134:137]
	v_mfma_f32_16x16x4_f32 v[138:141], v30, v126, v[138:141]
	v_mfma_f32_16x16x4_f32 v[134:137], v31, v95, v[134:137]
	v_mfma_f32_16x16x4_f32 v[138:141], v31, v127, v[138:141]
	v_mfma_f32_16x16x4_f32 v[134:137], v32, v96, v[134:137]
	v_mfma_f32_16x16x4_f32 v[138:141], v32, v128, v[138:141]
	v_mfma_f32_16x16x4_f32 v[134:137], v33, v97, v[134:137]
	v_mfma_f32_16x16x4_f32 v[138:141], v33, v129, v[138:141]
	v_mfma_f32_16x16x4_f32 v[134:137], v34, v98, v[134:137]
	v_mfma_f32_16x16x4_f32 v[138:141], v34, v130, v[138:141]
	v_mfma_f32_16x16x4_f32 v[134:137], v35, v99, v[134:137]
	v_mfma_f32_16x16x4_f32 v[138:141], v35, v131, v[138:141]
	v_mfma_f32_16x16x4_f32 v[134:137], v36, v100, v[134:137]
	v_mfma_f32_16x16x4_f32 v[138:141], v36, v132, v[138:141]
	v_mfma_f32_16x16x4_f32 v[134:137], v37, v101, v[134:137]
	v_mfma_f32_16x16x4_f32 v[138:141], v37, v133, v[138:141]
	s_nop 15
	s_nop 7
	v_cvt_pk_bf16_f32 v146, v134, v135
	v_cvt_pk_bf16_f32 v147, v136, v137
	v_cvt_pk_bf16_f32 v148, v138, v139
	v_cvt_pk_bf16_f32 v149, v140, v141
	global_store_dwordx2 v150, v[146:147], s[40:41]
	global_store_dwordx2 v150, v[148:149], s[44:45]
	s_cmp_lg_u32 s14, 0
	s_cbranch_scc1 .LBB0_79
	v_mul_f32_e32 v146, v38, v70
	v_mul_f32_e32 v147, v38, v102
	v_fmac_f32_e32 v146, v39, v71
	v_fmac_f32_e32 v147, v39, v103
	v_fmac_f32_e32 v146, v40, v72
	v_fmac_f32_e32 v147, v40, v104
	v_fmac_f32_e32 v146, v41, v73
	v_fmac_f32_e32 v147, v41, v105
	v_fmac_f32_e32 v146, v42, v74
	v_fmac_f32_e32 v147, v42, v106
	v_fmac_f32_e32 v146, v43, v75
	v_fmac_f32_e32 v147, v43, v107
	v_fmac_f32_e32 v146, v44, v76
	v_fmac_f32_e32 v147, v44, v108
	v_fmac_f32_e32 v146, v45, v77
	v_fmac_f32_e32 v147, v45, v109
	v_fmac_f32_e32 v146, v46, v78
	v_fmac_f32_e32 v147, v46, v110
	v_fmac_f32_e32 v146, v47, v79
	v_fmac_f32_e32 v147, v47, v111
	v_fmac_f32_e32 v146, v48, v80
	v_fmac_f32_e32 v147, v48, v112
	v_fmac_f32_e32 v146, v49, v81
	v_fmac_f32_e32 v147, v49, v113
	v_fmac_f32_e32 v146, v50, v82
	v_fmac_f32_e32 v147, v50, v114
	v_fmac_f32_e32 v146, v51, v83
	v_fmac_f32_e32 v147, v51, v115
	v_fmac_f32_e32 v146, v52, v84
	v_fmac_f32_e32 v147, v52, v116
	v_fmac_f32_e32 v146, v53, v85
	v_fmac_f32_e32 v147, v53, v117
	v_fmac_f32_e32 v146, v54, v86
	v_fmac_f32_e32 v147, v54, v118
	v_fmac_f32_e32 v146, v55, v87
	v_fmac_f32_e32 v147, v55, v119
	v_fmac_f32_e32 v146, v56, v88
	v_fmac_f32_e32 v147, v56, v120
	v_fmac_f32_e32 v146, v57, v89
	v_fmac_f32_e32 v147, v57, v121
	v_fmac_f32_e32 v146, v58, v90
	v_fmac_f32_e32 v147, v58, v122
	v_fmac_f32_e32 v146, v59, v91
	v_fmac_f32_e32 v147, v59, v123
	v_fmac_f32_e32 v146, v60, v92
	v_fmac_f32_e32 v147, v60, v124
	v_fmac_f32_e32 v146, v61, v93
	v_fmac_f32_e32 v147, v61, v125
	v_fmac_f32_e32 v146, v62, v94
	v_fmac_f32_e32 v147, v62, v126
	v_fmac_f32_e32 v146, v63, v95
	v_fmac_f32_e32 v147, v63, v127
	v_fmac_f32_e32 v146, v64, v96
	v_fmac_f32_e32 v147, v64, v128
	v_fmac_f32_e32 v146, v65, v97
	v_fmac_f32_e32 v147, v65, v129
	v_fmac_f32_e32 v146, v142, v98
	v_fmac_f32_e32 v147, v142, v130
	v_fmac_f32_e32 v146, v143, v99
	v_fmac_f32_e32 v147, v143, v131
	v_fmac_f32_e32 v146, v144, v100
	v_fmac_f32_e32 v147, v144, v132
	v_fmac_f32_e32 v146, v145, v101
	v_fmac_f32_e32 v147, v145, v133
	v_mov_b32_e32 v148, v146
	s_nop 1
	v_permlane16_swap_b32_e32 v148, v146
	s_nop 1
	v_add_f32_e32 v146, v148, v146
	v_mov_b32_e32 v148, v146
	s_nop 1
	v_permlane32_swap_b32_e32 v148, v146
	s_nop 1
	v_add_f32_e32 v146, v148, v146
	v_mov_b32_e32 v149, v147
	s_nop 1
	v_permlane16_swap_b32_e32 v149, v147
	s_nop 1
	v_add_f32_e32 v147, v149, v147
	v_mov_b32_e32 v149, v147
	s_nop 1
	v_permlane32_swap_b32_e32 v149, v147
	s_nop 1
	v_add_f32_e32 v147, v149, v147
	s_mul_i32 s46, s12, 0x1800000
	s_add_u32 s46, s46, 0x1981000
	s_lshl_b32 s47, s13, 12
	s_add_u32 s46, s46, s47
	s_lshl_b32 s47, s15, 7
	s_add_u32 s46, s46, s47
	s_add_u32 s46, s18, s46
	s_addc_u32 s47, s19, 0
	v_lshlrev_b32_e32 v148, 2, v3
	global_store_dword v148, v146, s[46:47]
	global_store_dword v148, v147, s[46:47] offset:64

.LBB0_106:
	s_cmp_lt_u32 s33, 0x40001
	s_mov_b64 s[48:49], 0
	s_cselect_b64 s[52:53], -1, 0
	s_and_b64 vcc, exec, s[52:53]
	s_cbranch_vccz .LBB0_99
	s_branch .LBB0_105
.LBB0_108:
	s_andn2_b64 vcc, exec, s[48:49]
	s_cbranch_vccz .LBB0_112
	s_mov_b64 s[16:17], exec
	v_mbcnt_lo_u32_b32 v16, s16, 0
	v_mbcnt_hi_u32_b32 v16, s17, v16
	v_cmp_eq_u32_e32 vcc, 0, v16
	s_and_saveexec_b64 s[12:13], vcc
	s_cbranch_execz .LBB0_111
	s_bcnt1_i32_b64 s11, s[16:17]
	v_mov_b32_e32 v16, 0
	v_mov_b32_e32 v17, s11
	global_atomic_add v16, v17, s[14:15]
